# skinny sample-row GEMM jobs: all operand loads issued before the first MFMA with counted vmcnt (was 4 serialized round trips per 128-deep K block, 6 more in the w_down tail); residual/row-sum load iss
# speedup vs baseline: 1.0626x; 1.0041x over previous
.LBB0_304:
	s_and_b32 s14, s8, 0x60
	s_and_b32 s15, s6, 0xffffffe0
	v_or_b32_e32 v2, s14, v22
	v_or_b32_e32 v0, s15, v22
	v_ashrrev_i32_e32 v1, 31, v0
	v_lshlrev_b32_e32 v16, 11, v2
	v_lshlrev_b64 v[0:1], 11, v[0:1]
	v_lshl_add_u64 v[4:5], v[20:21], 0, v[16:17]
	v_lshl_add_u64 v[68:69], v[18:19], 0, v[0:1]
	global_load_dwordx4 v[0:3], v[4:5], off
	global_load_dwordx4 v[32:35], v[4:5], off offset:32
	global_load_dwordx4 v[36:39], v[4:5], off offset:64
	global_load_dwordx4 v[40:43], v[4:5], off offset:96
	global_load_dwordx4 v[44:47], v[4:5], off offset:128
	global_load_dwordx4 v[48:51], v[4:5], off offset:160
	global_load_dwordx4 v[52:55], v[4:5], off offset:192
	global_load_dwordx4 v[56:59], v[4:5], off offset:224
	s_nop 0
	global_load_dwordx4 v[4:7], v[68:69], off
	global_load_dwordx4 v[60:63], v[68:69], off offset:32
	global_load_dwordx4 v[64:67], v[68:69], off offset:64
	global_load_dwordx4 v[160:163], v[68:69], off offset:96
	global_load_dwordx4 v[164:167], v[68:69], off offset:128
	global_load_dwordx4 v[168:171], v[68:69], off offset:160
	global_load_dwordx4 v[172:175], v[68:69], off offset:192
	global_load_dwordx4 v[176:179], v[68:69], off offset:224
	v_add_u32_e32 v16, s14, v24
	s_add_i32 s13, s13, s34
	s_add_i32 s6, s6, s7
	s_add_i32 s8, s8, s9
	s_cmpk_lt_i32 s13, 0x200
	s_waitcnt vmcnt(7)
	v_mfma_f32_32x32x16_bf16 v[0:15], v[0:3], v[4:7], 0
	s_waitcnt vmcnt(6)
	v_mfma_f32_32x32x16_bf16 v[0:15], v[32:35], v[60:63], v[0:15]
	s_waitcnt vmcnt(5)
	v_mfma_f32_32x32x16_bf16 v[0:15], v[36:39], v[64:67], v[0:15]
	s_waitcnt vmcnt(4)
	v_mfma_f32_32x32x16_bf16 v[0:15], v[40:43], v[160:163], v[0:15]
	s_waitcnt vmcnt(3)
	v_mfma_f32_32x32x16_bf16 v[0:15], v[44:47], v[164:167], v[0:15]
	s_waitcnt vmcnt(2)
	v_mfma_f32_32x32x16_bf16 v[0:15], v[48:51], v[168:171], v[0:15]
	s_waitcnt vmcnt(1)
	v_mfma_f32_32x32x16_bf16 v[0:15], v[52:55], v[172:175], v[0:15]
	v_lshlrev_b32_e32 v36, 2, v16
	v_lshlrev_b32_e32 v16, 13, v16
	s_waitcnt vmcnt(0)
	v_mfma_f32_32x32x16_bf16 v[0:15], v[56:59], v[176:179], v[0:15]
	global_load_dword v34, v36, s[2:3]
	s_nop 11
	ds_write2_b32 v23, v0, v1 offset1:32
	ds_write2_b32 v23, v2, v3 offset0:64 offset1:96
	ds_write2_b32 v28, v4, v5 offset1:32
	ds_write2_b32 v28, v6, v7 offset0:64 offset1:96
	ds_write2_b32 v29, v8, v9 offset1:32
	ds_write2_b32 v29, v10, v11 offset0:64 offset1:96
	ds_write2_b32 v30, v12, v13 offset1:32
	ds_write2_b32 v30, v14, v15 offset0:64 offset1:96
	s_waitcnt lgkmcnt(0)
	s_barrier
	v_or_b32_e32 v0, s15, v25
	v_ashrrev_i32_e32 v1, 31, v0
	v_lshl_add_u64 v[2:3], s[0:1], 0, v[16:17]
	v_lshl_add_u64 v[32:33], v[0:1], 1, v[2:3]
	ds_read2st64_b64 v[0:3], v26 offset1:8
	ds_read2st64_b64 v[4:7], v26 offset0:16 offset1:24
	ds_read2st64_b64 v[8:11], v26 offset0:32 offset1:40
	ds_read2st64_b64 v[12:15], v26 offset0:48 offset1:56
	s_waitcnt lgkmcnt(3)
	v_pk_add_f32 v[0:1], v[0:1], 0 op_sel_hi:[1,0]
	s_nop 0
	v_pk_add_f32 v[0:1], v[0:1], v[2:3]
	s_waitcnt vmcnt(0)
	v_fmamk_f32 v2, v34, 0x3a800000, v27
	v_mul_f32_e32 v3, 0x4b800000, v2
	v_cmp_gt_f32_e32 vcc, s10, v2
	s_waitcnt lgkmcnt(2)
	v_pk_add_f32 v[0:1], v[0:1], v[4:5]
	v_cndmask_b32_e32 v2, v2, v3, vcc
	v_rsq_f32_e32 v2, v2
	v_pk_add_f32 v[0:1], v[0:1], v[6:7]
	v_mul_f32_e32 v3, 0x45800000, v2
	s_waitcnt lgkmcnt(1)
	v_pk_add_f32 v[0:1], v[0:1], v[8:9]
	v_cndmask_b32_e32 v2, v2, v3, vcc
	v_pk_add_f32 v[0:1], v[0:1], v[10:11]
	s_waitcnt lgkmcnt(0)
	v_pk_add_f32 v[0:1], v[0:1], v[12:13]
	s_nop 0
	v_pk_add_f32 v[0:1], v[0:1], v[14:15]
	s_nop 0
	v_pk_mul_f32 v[0:1], v[0:1], v[2:3] op_sel_hi:[1,0]
	s_nop 0
	v_and_b32_sdwa v3, v0, v31 dst_sel:DWORD dst_unused:UNUSED_PAD src0_sel:WORD_1 src1_sel:DWORD
	v_and_b32_sdwa v2, v1, v31 dst_sel:DWORD dst_unused:UNUSED_PAD src0_sel:WORD_1 src1_sel:DWORD
	v_add3_u32 v0, v0, v3, s11
	v_add3_u32 v1, v1, v2, s11
	v_lshrrev_b32_e32 v0, 16, v0
	v_and_or_b32 v0, v1, s12, v0
	global_store_dword v[32:33], v0, off
	s_barrier
	s_cbranch_scc1 .LBB0_304

.LBB0_1016:
	s_and_b32 s0, s10, 0x60
	v_or_b32_e32 v0, s0, v22
	v_lshlrev_b32_e32 v16, 11, v0
	v_lshl_add_u64 v[54:55], v[18:19], 0, v[16:17]
	global_load_dwordx4 v[0:3], v[54:55], off
	s_and_b32 s1, s8, 0xffffffe0
	v_or_b32_e32 v4, s1, v22
	v_ashrrev_i32_e32 v5, 31, v4
	v_lshlrev_b64 v[4:5], 11, v[4:5]
	v_lshl_add_u64 v[56:57], v[20:21], 0, v[4:5]
	global_load_dwordx4 v[4:7], v[56:57], off
	global_load_dwordx4 v[34:37], v[54:55], off offset:32
	global_load_dwordx4 v[38:41], v[56:57], off offset:32
	global_load_dwordx4 v[42:45], v[54:55], off offset:64
	global_load_dwordx4 v[46:49], v[56:57], off offset:64
	global_load_dwordx4 v[50:53], v[54:55], off offset:96
	global_load_dwordx4 v[160:163], v[56:57], off offset:96
	global_load_dwordx4 v[164:167], v[54:55], off offset:128
	global_load_dwordx4 v[168:171], v[56:57], off offset:128
	global_load_dwordx4 v[172:175], v[54:55], off offset:160
	global_load_dwordx4 v[176:179], v[56:57], off offset:160
	global_load_dwordx4 v[180:183], v[54:55], off offset:192
	global_load_dwordx4 v[184:187], v[56:57], off offset:192
	global_load_dwordx4 v[188:191], v[54:55], off offset:224
	global_load_dwordx4 v[192:195], v[56:57], off offset:224
	v_readlane_b32 s36, v255, 1
	v_readlane_b32 s38, v255, 3
	v_readlane_b32 s39, v255, 4
	v_readlane_b32 s37, v255, 2
	v_readlane_b32 s40, v255, 5
	v_readlane_b32 s41, v255, 6
	v_readlane_b32 s42, v255, 7
	v_readlane_b32 s43, v255, 8
	v_readlane_b32 s44, v255, 9
	v_readlane_b32 s45, v255, 10
	v_readlane_b32 s46, v255, 11
	v_readlane_b32 s47, v255, 12
	v_readlane_b32 s48, v255, 13
	v_readlane_b32 s49, v255, 14
	v_readlane_b32 s50, v255, 15
	v_readlane_b32 s51, v255, 16
	s_waitcnt vmcnt(14)
	v_mfma_f32_32x32x16_bf16 v[0:15], v[0:3], v[4:7], 0
	s_waitcnt vmcnt(12)
	v_mfma_f32_32x32x16_bf16 v[0:15], v[34:37], v[38:41], v[0:15]
	s_waitcnt vmcnt(10)
	v_mfma_f32_32x32x16_bf16 v[0:15], v[42:45], v[46:49], v[0:15]
	s_waitcnt vmcnt(8)
	v_mfma_f32_32x32x16_bf16 v[0:15], v[50:53], v[160:163], v[0:15]
	s_waitcnt vmcnt(6)
	v_mfma_f32_32x32x16_bf16 v[0:15], v[164:167], v[168:171], v[0:15]
	s_waitcnt vmcnt(4)
	v_mfma_f32_32x32x16_bf16 v[0:15], v[172:175], v[176:179], v[0:15]
	v_add_u32_e32 v34, s0, v150
	v_or_b32_e32 v36, s1, v24
	v_ashrrev_i32_e32 v37, 31, v36
	v_lshlrev_b32_e32 v16, 10, v34
	v_lshl_add_u64 v[36:37], v[16:17], 0, v[36:37]
	s_waitcnt vmcnt(2)
	v_mfma_f32_32x32x16_bf16 v[0:15], v[180:183], v[184:187], v[0:15]
	v_lshl_add_u64 v[38:39], v[36:37], 2, s[38:39]
	s_waitcnt vmcnt(0)
	v_mfma_f32_32x32x16_bf16 v[0:15], v[188:191], v[192:195], v[0:15]
	global_load_dwordx2 v[38:39], v[38:39], off
	s_nop 11
	ds_write2_b32 v23, v0, v1 offset1:32
	ds_write2_b32 v23, v2, v3 offset0:64 offset1:96
	ds_write2_b32 v30, v4, v5 offset1:32
	ds_write2_b32 v30, v6, v7 offset0:64 offset1:96
	ds_write2_b32 v31, v8, v9 offset1:32
	ds_write2_b32 v31, v10, v11 offset0:64 offset1:96
	ds_write2_b32 v32, v12, v13 offset1:32
	ds_write2_b32 v32, v14, v15 offset0:64 offset1:96
	s_waitcnt lgkmcnt(0)
	s_barrier
	ds_read2st64_b64 v[0:3], v25 offset1:8
	ds_read2st64_b64 v[4:7], v25 offset0:16 offset1:24
	ds_read2st64_b64 v[8:11], v25 offset0:32 offset1:40
	ds_read2st64_b64 v[12:15], v25 offset0:48 offset1:56
	s_waitcnt lgkmcnt(3)
	v_pk_add_f32 v[0:1], v[0:1], 0 op_sel_hi:[1,0]
	s_nop 0
	v_pk_add_f32 v[0:1], v[0:1], v[2:3]
	s_waitcnt lgkmcnt(2)
	v_pk_add_f32 v[0:1], v[0:1], v[4:5]
	s_nop 0
	v_pk_add_f32 v[0:1], v[0:1], v[6:7]
	s_waitcnt lgkmcnt(1)
	v_pk_add_f32 v[0:1], v[0:1], v[8:9]
	s_nop 0
	v_pk_add_f32 v[0:1], v[0:1], v[10:11]
	s_waitcnt lgkmcnt(0)
	v_pk_add_f32 v[0:1], v[0:1], v[12:13]
	s_nop 0
	v_pk_add_f32 v[0:1], v[0:1], v[14:15]
	s_waitcnt vmcnt(0)
	v_pk_add_f32 v[0:1], v[0:1], v[38:39]
	s_nop 0
	v_pk_mul_f32 v[2:3], v[0:1], v[0:1]
	v_and_b32_sdwa v5, v0, v33 dst_sel:DWORD dst_unused:UNUSED_PAD src0_sel:WORD_1 src1_sel:DWORD
	v_add_f32_e32 v2, v2, v3
	ds_bpermute_b32 v3, v26, v2
	v_and_b32_sdwa v4, v1, v33 dst_sel:DWORD dst_unused:UNUSED_PAD src0_sel:WORD_1 src1_sel:DWORD
	v_add3_u32 v5, v0, v5, s12
	v_add3_u32 v4, v1, v4, s12
	s_waitcnt lgkmcnt(0)
	v_add_f32_e32 v2, v2, v3
	ds_bpermute_b32 v3, v27, v2
	s_waitcnt lgkmcnt(0)
	v_add_f32_e32 v2, v2, v3
	ds_bpermute_b32 v3, v28, v2
	s_waitcnt lgkmcnt(0)
	v_add_f32_e32 v0, v2, v3
	ds_bpermute_b32 v1, v29, v0
	v_lshrrev_b32_e32 v2, 16, v5
	v_and_or_b32 v4, v4, s13, v2
	v_lshl_add_u64 v[2:3], v[36:37], 1, s[2:3]
	global_store_dword v[2:3], v4, off
	s_and_saveexec_b64 s[0:1], vcc
	s_cbranch_execz .LBB0_1015
	v_lshlrev_b32_e32 v2, 2, v34
	s_waitcnt lgkmcnt(0)
	v_add_f32_e32 v0, v0, v1
	global_atomic_add_f32 v2, v0, s[4:5]
	s_branch .LBB0_1015

.LBB0_1095:
	s_and_b32 s14, s8, 0x60
	s_and_b32 s15, s6, 0xffffffe0
	v_or_b32_e32 v2, s14, v22
	v_or_b32_e32 v0, s15, v22
	v_ashrrev_i32_e32 v1, 31, v0
	v_lshlrev_b32_e32 v16, 11, v2
	v_lshlrev_b64 v[0:1], 11, v[0:1]
	v_lshl_add_u64 v[8:9], v[18:19], 0, v[16:17]
	v_lshl_add_u64 v[68:69], v[20:21], 0, v[0:1]
	global_load_dwordx4 v[0:3], v[8:9], off
	global_load_dwordx4 v[32:35], v[8:9], off offset:32
	global_load_dwordx4 v[36:39], v[8:9], off offset:64
	global_load_dwordx4 v[40:43], v[8:9], off offset:96
	global_load_dwordx4 v[44:47], v[8:9], off offset:128
	global_load_dwordx4 v[48:51], v[8:9], off offset:160
	global_load_dwordx4 v[52:55], v[8:9], off offset:192
	global_load_dwordx4 v[56:59], v[8:9], off offset:224
	global_load_dwordx4 v[4:7], v[68:69], off
	global_load_dwordx4 v[60:63], v[68:69], off offset:32
	global_load_dwordx4 v[64:67], v[68:69], off offset:64
	global_load_dwordx4 v[160:163], v[68:69], off offset:96
	global_load_dwordx4 v[164:167], v[68:69], off offset:128
	global_load_dwordx4 v[168:171], v[68:69], off offset:160
	global_load_dwordx4 v[172:175], v[68:69], off offset:192
	global_load_dwordx4 v[176:179], v[68:69], off offset:224
	v_add_u32_e32 v16, s14, v24
	s_add_i32 s13, s13, s34
	s_add_i32 s6, s6, s7
	s_add_i32 s8, s8, s9
	s_cmpk_lt_i32 s13, 0x80
	s_waitcnt vmcnt(7)
	v_mfma_f32_32x32x16_bf16 v[0:15], v[0:3], v[4:7], 0
	s_waitcnt vmcnt(6)
	v_mfma_f32_32x32x16_bf16 v[0:15], v[32:35], v[60:63], v[0:15]
	s_waitcnt vmcnt(5)
	v_mfma_f32_32x32x16_bf16 v[0:15], v[36:39], v[64:67], v[0:15]
	s_waitcnt vmcnt(4)
	v_mfma_f32_32x32x16_bf16 v[0:15], v[40:43], v[160:163], v[0:15]
	s_waitcnt vmcnt(3)
	v_mfma_f32_32x32x16_bf16 v[0:15], v[44:47], v[164:167], v[0:15]
	s_waitcnt vmcnt(2)
	v_mfma_f32_32x32x16_bf16 v[0:15], v[48:51], v[168:171], v[0:15]
	s_waitcnt vmcnt(1)
	v_mfma_f32_32x32x16_bf16 v[0:15], v[52:55], v[172:175], v[0:15]
	v_lshlrev_b32_e32 v36, 2, v16
	v_lshlrev_b32_e32 v16, 11, v16
	s_waitcnt vmcnt(0)
	v_mfma_f32_32x32x16_bf16 v[0:15], v[56:59], v[176:179], v[0:15]
	global_load_dword v34, v36, s[2:3]
	s_nop 11
	ds_write2_b32 v23, v0, v1 offset1:32
	ds_write2_b32 v23, v2, v3 offset0:64 offset1:96
	ds_write2_b32 v28, v4, v5 offset1:32
	ds_write2_b32 v28, v6, v7 offset0:64 offset1:96
	ds_write2_b32 v29, v8, v9 offset1:32
	ds_write2_b32 v29, v10, v11 offset0:64 offset1:96
	ds_write2_b32 v30, v12, v13 offset1:32
	ds_write2_b32 v30, v14, v15 offset0:64 offset1:96
	s_waitcnt lgkmcnt(0)
	s_barrier
	v_or_b32_e32 v0, s15, v25
	v_ashrrev_i32_e32 v1, 31, v0
	v_lshl_add_u64 v[2:3], s[0:1], 0, v[16:17]
	v_lshl_add_u64 v[32:33], v[0:1], 1, v[2:3]
	ds_read2st64_b64 v[0:3], v26 offset1:8
	ds_read2st64_b64 v[4:7], v26 offset0:16 offset1:24
	ds_read2st64_b64 v[8:11], v26 offset0:32 offset1:40
	ds_read2st64_b64 v[12:15], v26 offset0:48 offset1:56
	s_waitcnt lgkmcnt(3)
	v_pk_add_f32 v[0:1], v[0:1], 0 op_sel_hi:[1,0]
	s_nop 0
	v_pk_add_f32 v[0:1], v[0:1], v[2:3]
	s_waitcnt vmcnt(0)
	v_fmamk_f32 v2, v34, 0x3a800000, v27
	v_mul_f32_e32 v3, 0x4b800000, v2
	v_cmp_gt_f32_e32 vcc, s10, v2
	s_waitcnt lgkmcnt(2)
	v_pk_add_f32 v[0:1], v[0:1], v[4:5]
	v_cndmask_b32_e32 v2, v2, v3, vcc
	v_rsq_f32_e32 v2, v2
	v_pk_add_f32 v[0:1], v[0:1], v[6:7]
	v_mul_f32_e32 v3, 0x45800000, v2
	s_waitcnt lgkmcnt(1)
	v_pk_add_f32 v[0:1], v[0:1], v[8:9]
	v_cndmask_b32_e32 v2, v2, v3, vcc
	v_pk_add_f32 v[0:1], v[0:1], v[10:11]
	v_mul_f32_e32 v2, 0x3d800000, v2
	s_waitcnt lgkmcnt(0)
	v_pk_add_f32 v[0:1], v[0:1], v[12:13]
	s_nop 0
	v_pk_add_f32 v[0:1], v[0:1], v[14:15]
	s_nop 0
	v_pk_mul_f32 v[0:1], v[0:1], v[2:3] op_sel_hi:[1,0]
	s_nop 0
	v_and_b32_sdwa v3, v0, v31 dst_sel:DWORD dst_unused:UNUSED_PAD src0_sel:WORD_1 src1_sel:DWORD
	v_and_b32_sdwa v2, v1, v31 dst_sel:DWORD dst_unused:UNUSED_PAD src0_sel:WORD_1 src1_sel:DWORD
	v_add3_u32 v0, v0, v3, s11
	v_add3_u32 v1, v1, v2, s11
	v_lshrrev_b32_e32 v0, 16, v0
	v_and_or_b32 v0, v1, s12, v0
	global_store_dword v[32:33], v0, off
	s_barrier
	s_cbranch_scc1 .LBB0_1095

.LBB0_1272:
	s_and_b32 s0, s10, 0x60
	v_or_b32_e32 v0, s0, v22
	v_lshlrev_b32_e32 v16, 11, v0
	v_lshl_add_u64 v[54:55], v[18:19], 0, v[16:17]
	global_load_dwordx4 v[0:3], v[54:55], off
	s_and_b32 s1, s8, 0xffffffe0
	v_or_b32_e32 v4, s1, v22
	v_ashrrev_i32_e32 v5, 31, v4
	v_lshlrev_b64 v[4:5], 11, v[4:5]
	v_lshl_add_u64 v[56:57], v[20:21], 0, v[4:5]
	global_load_dwordx4 v[4:7], v[56:57], off
	global_load_dwordx4 v[34:37], v[54:55], off offset:32
	global_load_dwordx4 v[38:41], v[56:57], off offset:32
	global_load_dwordx4 v[42:45], v[54:55], off offset:64
	global_load_dwordx4 v[46:49], v[56:57], off offset:64
	global_load_dwordx4 v[50:53], v[54:55], off offset:96
	global_load_dwordx4 v[160:163], v[56:57], off offset:96
	global_load_dwordx4 v[164:167], v[54:55], off offset:128
	global_load_dwordx4 v[168:171], v[56:57], off offset:128
	global_load_dwordx4 v[172:175], v[54:55], off offset:160
	global_load_dwordx4 v[176:179], v[56:57], off offset:160
	global_load_dwordx4 v[180:183], v[54:55], off offset:192
	global_load_dwordx4 v[184:187], v[56:57], off offset:192
	global_load_dwordx4 v[188:191], v[54:55], off offset:224
	global_load_dwordx4 v[192:195], v[56:57], off offset:224
	s_waitcnt vmcnt(14)
	v_mfma_f32_32x32x16_bf16 v[0:15], v[0:3], v[4:7], 0
	s_waitcnt vmcnt(12)
	v_mfma_f32_32x32x16_bf16 v[0:15], v[34:37], v[38:41], v[0:15]
	s_waitcnt vmcnt(10)
	v_mfma_f32_32x32x16_bf16 v[0:15], v[42:45], v[46:49], v[0:15]
	s_waitcnt vmcnt(8)
	v_mfma_f32_32x32x16_bf16 v[0:15], v[50:53], v[160:163], v[0:15]
	s_waitcnt vmcnt(6)
	v_mfma_f32_32x32x16_bf16 v[0:15], v[164:167], v[168:171], v[0:15]
	s_waitcnt vmcnt(4)
	v_mfma_f32_32x32x16_bf16 v[0:15], v[172:175], v[176:179], v[0:15]
	v_add_u32_e32 v34, s0, v150
	v_or_b32_e32 v36, s1, v24
	v_lshlrev_b32_e32 v16, 11, v34
	v_ashrrev_i32_e32 v37, 31, v36
	s_waitcnt vmcnt(2)
	v_mfma_f32_32x32x16_bf16 v[0:15], v[180:183], v[184:187], v[0:15]
	v_lshl_add_u64 v[38:39], s[2:3], 0, v[16:17]
	v_lshl_add_u64 v[36:37], v[36:37], 1, v[38:39]
	s_waitcnt vmcnt(0)
	v_mfma_f32_32x32x16_bf16 v[0:15], v[188:191], v[192:195], v[0:15]
	global_load_dword v16, v[36:37], off
	s_nop 11
	ds_write2_b32 v23, v0, v1 offset1:32
	ds_write2_b32 v23, v2, v3 offset0:64 offset1:96
	ds_write2_b32 v30, v4, v5 offset1:32
	ds_write2_b32 v30, v6, v7 offset0:64 offset1:96
	ds_write2_b32 v31, v8, v9 offset1:32
	ds_write2_b32 v31, v10, v11 offset0:64 offset1:96
	ds_write2_b32 v32, v12, v13 offset1:32
	ds_write2_b32 v32, v14, v15 offset0:64 offset1:96
	s_waitcnt lgkmcnt(0)
	s_barrier
	ds_read2st64_b64 v[0:3], v25 offset1:8
	ds_read2st64_b64 v[4:7], v25 offset0:16 offset1:24
	ds_read2st64_b64 v[8:11], v25 offset0:32 offset1:40
	ds_read2st64_b64 v[12:15], v25 offset0:48 offset1:56
	s_waitcnt lgkmcnt(3)
	v_pk_add_f32 v[0:1], v[0:1], 0 op_sel_hi:[1,0]
	s_nop 0
	v_pk_add_f32 v[0:1], v[0:1], v[2:3]
	s_waitcnt vmcnt(0)
	v_lshlrev_b32_e32 v2, 16, v16
	s_waitcnt lgkmcnt(2)
	v_pk_add_f32 v[0:1], v[0:1], v[4:5]
	v_and_b32_e32 v3, 0xffff0000, v16
	v_pk_add_f32 v[0:1], v[0:1], v[6:7]
	s_waitcnt lgkmcnt(1)
	v_pk_add_f32 v[0:1], v[0:1], v[8:9]
	s_nop 0
	v_pk_add_f32 v[0:1], v[0:1], v[10:11]
	s_waitcnt lgkmcnt(0)
	v_pk_add_f32 v[0:1], v[0:1], v[12:13]
	s_nop 0
	v_pk_add_f32 v[0:1], v[0:1], v[14:15]
	s_nop 0
	v_pk_add_f32 v[2:3], v[0:1], v[2:3]
	s_nop 0
	v_pk_mul_f32 v[0:1], v[2:3], v[2:3]
	v_and_b32_sdwa v5, v2, v33 dst_sel:DWORD dst_unused:UNUSED_PAD src0_sel:WORD_1 src1_sel:DWORD
	v_add_f32_e32 v0, v1, v0
	ds_bpermute_b32 v1, v26, v0
	v_and_b32_sdwa v4, v3, v33 dst_sel:DWORD dst_unused:UNUSED_PAD src0_sel:WORD_1 src1_sel:DWORD
	v_add3_u32 v2, v2, v5, s13
	v_add3_u32 v3, v3, v4, s13
	v_lshrrev_b32_e32 v2, 16, v2
	s_waitcnt lgkmcnt(0)
	v_add_f32_e32 v0, v0, v1
	ds_bpermute_b32 v1, v27, v0
	v_and_or_b32 v2, v3, s12, v2
	global_store_dword v[36:37], v2, off
	s_waitcnt lgkmcnt(0)
	v_add_f32_e32 v0, v0, v1
	ds_bpermute_b32 v1, v28, v0
	s_waitcnt lgkmcnt(0)
	v_add_f32_e32 v0, v0, v1
	ds_bpermute_b32 v1, v29, v0
	s_and_saveexec_b64 s[0:1], vcc
	s_cbranch_execz .LBB0_1271
	v_lshlrev_b32_e32 v2, 2, v34
	s_waitcnt lgkmcnt(0)
	v_add_f32_e32 v0, v0, v1
	global_atomic_add_f32 v2, v0, s[4:5]
	s_branch .LBB0_1271

.LBB0_1449:
	s_and_b32 s10, s12, 0xffffffe0
	v_or_b32_e32 v0, s10, v32
	v_mad_i64_i32 v[26:27], s[10:11], v0, s14, 0
	v_mad_i64_i32 v[28:29], s[10:11], v0, s14, v[18:19]
	s_lshl_b32 s10, s17, 5
	s_and_b32 s10, s10, 0x60
	v_or_b32_e32 v0, s10, v32
	v_mul_u32_u24_e32 v0, 0xb00, v0
	v_lshlrev_b32_e32 v16, 1, v0
	v_lshl_add_u64 v[30:31], v[20:21], 0, v[16:17]
	s_mov_b32 s11, 0
	v_mov_b32_e32 v0, v17
	v_mov_b32_e32 v1, v17
	v_mov_b32_e32 v2, v17
	v_mov_b32_e32 v3, v17
	v_mov_b32_e32 v4, v17
	v_mov_b32_e32 v5, v17
	v_mov_b32_e32 v6, v17
	v_mov_b32_e32 v7, v17
	v_mov_b32_e32 v8, v17
	v_mov_b32_e32 v9, v17
	v_mov_b32_e32 v10, v17
	v_mov_b32_e32 v11, v17
	v_mov_b32_e32 v12, v17
	v_mov_b32_e32 v13, v17
	v_mov_b32_e32 v14, v17
	v_mov_b32_e32 v15, v17
	global_load_dwordx4 v[62:65], v[30:31], off offset:-128
	global_load_dwordx4 v[154:157], v[28:29], off offset:-128
	global_load_dwordx4 v[66:69], v[30:31], off offset:-96
	global_load_dwordx4 v[158:161], v[28:29], off offset:-96
	global_load_dwordx4 v[70:73], v[30:31], off offset:-64
	global_load_dwordx4 v[162:165], v[28:29], off offset:-64
	global_load_dwordx4 v[74:77], v[30:31], off offset:-32
	global_load_dwordx4 v[166:169], v[28:29], off offset:-32
	global_load_dwordx4 v[78:81], v[30:31], off offset:0
	global_load_dwordx4 v[170:173], v[28:29], off offset:0
	global_load_dwordx4 v[82:85], v[30:31], off offset:32
	global_load_dwordx4 v[174:177], v[28:29], off offset:32
	global_load_dwordx4 v[86:89], v[30:31], off offset:64
	global_load_dwordx4 v[178:181], v[28:29], off offset:64
	global_load_dwordx4 v[90:93], v[30:31], off offset:96
	global_load_dwordx4 v[182:185], v[28:29], off offset:96
	global_load_dwordx4 v[94:97], v[30:31], off offset:128
	global_load_dwordx4 v[186:189], v[28:29], off offset:128
	global_load_dwordx4 v[98:101], v[30:31], off offset:160
	global_load_dwordx4 v[190:193], v[28:29], off offset:160
	global_load_dwordx4 v[102:105], v[30:31], off offset:192
	global_load_dwordx4 v[194:197], v[28:29], off offset:192
	global_load_dwordx4 v[106:109], v[30:31], off offset:224
	global_load_dwordx4 v[198:201], v[28:29], off offset:224
	global_load_dwordx4 v[110:113], v[30:31], off offset:256
	global_load_dwordx4 v[202:205], v[28:29], off offset:256
	global_load_dwordx4 v[114:117], v[30:31], off offset:288
	global_load_dwordx4 v[206:209], v[28:29], off offset:288
	global_load_dwordx4 v[118:121], v[30:31], off offset:320
	global_load_dwordx4 v[210:213], v[28:29], off offset:320
	global_load_dwordx4 v[122:125], v[30:31], off offset:352
	global_load_dwordx4 v[214:217], v[28:29], off offset:352
	s_waitcnt vmcnt(30)
	v_mfma_f32_32x32x16_bf16 v[0:15], v[62:65], v[154:157], v[0:15]
	global_load_dwordx4 v[62:65], v[30:31], off offset:384
	global_load_dwordx4 v[154:157], v[28:29], off offset:384
	s_waitcnt vmcnt(30)
	v_mfma_f32_32x32x16_bf16 v[0:15], v[66:69], v[158:161], v[0:15]
	global_load_dwordx4 v[66:69], v[30:31], off offset:416
	global_load_dwordx4 v[158:161], v[28:29], off offset:416
	s_waitcnt vmcnt(30)
	v_mfma_f32_32x32x16_bf16 v[0:15], v[70:73], v[162:165], v[0:15]
	global_load_dwordx4 v[70:73], v[30:31], off offset:448
	global_load_dwordx4 v[162:165], v[28:29], off offset:448
	s_waitcnt vmcnt(30)
	v_mfma_f32_32x32x16_bf16 v[0:15], v[74:77], v[166:169], v[0:15]
	global_load_dwordx4 v[74:77], v[30:31], off offset:480
	global_load_dwordx4 v[166:169], v[28:29], off offset:480
	s_waitcnt vmcnt(30)
	v_mfma_f32_32x32x16_bf16 v[0:15], v[78:81], v[170:173], v[0:15]
	global_load_dwordx4 v[78:81], v[30:31], off offset:512
	global_load_dwordx4 v[170:173], v[28:29], off offset:512
	s_waitcnt vmcnt(30)
	v_mfma_f32_32x32x16_bf16 v[0:15], v[82:85], v[174:177], v[0:15]
	global_load_dwordx4 v[82:85], v[30:31], off offset:544
	global_load_dwordx4 v[174:177], v[28:29], off offset:544
	s_waitcnt vmcnt(30)
	v_mfma_f32_32x32x16_bf16 v[0:15], v[86:89], v[178:181], v[0:15]
	s_waitcnt vmcnt(28)
	v_mfma_f32_32x32x16_bf16 v[0:15], v[90:93], v[182:185], v[0:15]
	s_waitcnt vmcnt(26)
	v_mfma_f32_32x32x16_bf16 v[0:15], v[94:97], v[186:189], v[0:15]
	s_waitcnt vmcnt(24)
	v_mfma_f32_32x32x16_bf16 v[0:15], v[98:101], v[190:193], v[0:15]
	s_waitcnt vmcnt(22)
	v_mfma_f32_32x32x16_bf16 v[0:15], v[102:105], v[194:197], v[0:15]
	s_waitcnt vmcnt(20)
	v_mfma_f32_32x32x16_bf16 v[0:15], v[106:109], v[198:201], v[0:15]
	s_waitcnt vmcnt(18)
	v_mfma_f32_32x32x16_bf16 v[0:15], v[110:113], v[202:205], v[0:15]
	s_waitcnt vmcnt(16)
	v_mfma_f32_32x32x16_bf16 v[0:15], v[114:117], v[206:209], v[0:15]
	s_waitcnt vmcnt(14)
	v_mfma_f32_32x32x16_bf16 v[0:15], v[118:121], v[210:213], v[0:15]
	s_waitcnt vmcnt(12)
	v_mfma_f32_32x32x16_bf16 v[0:15], v[122:125], v[214:217], v[0:15]
	s_waitcnt vmcnt(10)
	v_mfma_f32_32x32x16_bf16 v[0:15], v[62:65], v[154:157], v[0:15]
	s_waitcnt vmcnt(8)
	v_mfma_f32_32x32x16_bf16 v[0:15], v[66:69], v[158:161], v[0:15]
	s_waitcnt vmcnt(6)
	v_mfma_f32_32x32x16_bf16 v[0:15], v[70:73], v[162:165], v[0:15]
	s_waitcnt vmcnt(4)
	v_mfma_f32_32x32x16_bf16 v[0:15], v[74:77], v[166:169], v[0:15]
	s_waitcnt vmcnt(2)
	v_mfma_f32_32x32x16_bf16 v[0:15], v[78:81], v[170:173], v[0:15]
	s_waitcnt vmcnt(0)
	v_mfma_f32_32x32x16_bf16 v[0:15], v[82:85], v[174:177], v[0:15]
	s_nop 10
	ds_write2_b32 v33, v0, v1 offset1:32
	ds_write2_b32 v33, v2, v3 offset0:64 offset1:96
	v_add_u32_e32 v0, 0x400, v33
	s_lshl_b32 s11, s17, 3
	ds_write2_b32 v0, v4, v5 offset1:32
	ds_write2_b32 v0, v6, v7 offset0:64 offset1:96
	v_add_u32_e32 v0, 0x800, v33
	s_andn2_b32 s11, s11, 31
	ds_write2_b32 v0, v8, v9 offset1:32
	ds_write2_b32 v0, v10, v11 offset0:64 offset1:96
	v_add_u32_e32 v0, 0xc00, v33
	ds_write2_b32 v0, v12, v13 offset1:32
	ds_write2_b32 v0, v14, v15 offset0:64 offset1:96
	v_add_u32_e32 v0, s10, v150
	v_or_b32_e32 v2, s11, v34
	v_lshlrev_b32_e32 v16, 10, v0
	v_ashrrev_i32_e32 v3, 31, v2
	v_lshl_add_u64 v[2:3], v[16:17], 0, v[2:3]
	v_lshlrev_b64 v[14:15], 1, v[2:3]
	v_lshl_add_u64 v[2:3], s[2:3], 0, v[14:15]
	global_load_dword v1, v[2:3], off
	s_waitcnt lgkmcnt(0)
	s_barrier
	ds_read2st64_b64 v[2:5], v35 offset1:8
	ds_read2st64_b64 v[6:9], v35 offset0:16 offset1:24
	ds_read2st64_b64 v[10:13], v35 offset0:32 offset1:40
	ds_read2st64_b64 v[26:29], v35 offset0:48 offset1:56
	s_waitcnt lgkmcnt(3)
	v_pk_add_f32 v[2:3], v[2:3], 0 op_sel_hi:[1,0]
	s_nop 0
	v_pk_add_f32 v[2:3], v[2:3], v[4:5]
	s_waitcnt vmcnt(0)
	v_lshlrev_b32_e32 v4, 16, v1
	s_waitcnt lgkmcnt(2)
	v_pk_add_f32 v[2:3], v[2:3], v[6:7]
	v_and_b32_e32 v5, 0xffff0000, v1
	v_pk_add_f32 v[2:3], v[2:3], v[8:9]
	s_waitcnt lgkmcnt(1)
	v_pk_add_f32 v[2:3], v[2:3], v[10:11]
	s_nop 0
	v_pk_add_f32 v[2:3], v[2:3], v[12:13]
	s_waitcnt lgkmcnt(0)
	v_pk_add_f32 v[2:3], v[2:3], v[26:27]
	s_nop 0
	v_pk_add_f32 v[2:3], v[2:3], v[28:29]
	s_nop 0
	v_pk_add_f32 v[2:3], v[2:3], v[4:5]
	s_nop 0
	v_pk_mul_f32 v[4:5], v[2:3], v[2:3]
	v_and_b32_sdwa v6, v2, v40 dst_sel:DWORD dst_unused:UNUSED_PAD src0_sel:WORD_1 src1_sel:DWORD
	v_add_f32_e32 v1, v5, v4
	ds_bpermute_b32 v4, v36, v1
	v_and_b32_sdwa v5, v3, v40 dst_sel:DWORD dst_unused:UNUSED_PAD src0_sel:WORD_1 src1_sel:DWORD
	v_add3_u32 v3, v3, v5, s16
	v_add3_u32 v5, v2, v6, s16
	s_waitcnt lgkmcnt(0)
	v_add_f32_e32 v1, v1, v4
	ds_bpermute_b32 v4, v37, v1
	s_waitcnt lgkmcnt(0)
	v_add_f32_e32 v1, v1, v4
	ds_bpermute_b32 v4, v38, v1
	s_waitcnt lgkmcnt(0)
	v_add_f32_e32 v1, v1, v4
	ds_bpermute_b32 v2, v39, v1
	v_lshrrev_b32_e32 v4, 16, v5
	v_and_or_b32 v3, v3, s15, v4
	v_lshl_add_u64 v[4:5], s[4:5], 0, v[14:15]
	global_store_dword v[4:5], v3, off
	s_and_saveexec_b64 s[10:11], vcc
	s_cbranch_execz .LBB0_1448
	v_lshlrev_b32_e32 v0, 2, v0
	s_waitcnt lgkmcnt(0)
	v_add_f32_e32 v1, v1, v2
	global_atomic_add_f32 v0, v1, s[8:9]
	s_branch .LBB0_1448
